# retention: 16 two-lane row-sum stores -> one 32-lane store (DPP gather), fewer VALU
# speedup vs baseline: 1.0103x; 1.0103x over previous
.LBB0_612:
	v_mul_f32_e32 v4, v228, v3
	v_exp_f32_e32 v7, v4
	v_lshl_add_u64 v[4:5], s[82:83], 0, v[184:185]
	v_add_co_u32_e32 v6, vcc, 0xfa00000, v4
	v_mul_f32_e32 v8, v176, v7
	v_mul_f32_e32 v8, v50, v8
	s_nop 1
	v_fmac_f32_e32 v8, v66, v7
	v_bfe_u32 v7, v8, 16, 1
	v_add3_u32 v9, v8, v7, s1
	v_mul_f32_e32 v7, v229, v3
	v_exp_f32_e32 v10, v7
	v_addc_co_u32_e32 v7, vcc, 0, v5, vcc
	global_store_short_d16_hi v[6:7], v9, off
	v_mul_f32_e32 v7, v230, v3
	v_exp_f32_e32 v12, v7
	v_mul_f32_e32 v6, v176, v10
	v_mul_f32_e32 v11, v51, v6
	v_mul_f32_e32 v14, v231, v3
	v_mul_f32_e32 v13, v176, v12
	v_fmac_f32_e32 v11, v67, v10
	v_mul_f32_e32 v13, v52, v13
	v_exp_f32_e32 v14, v14
	v_bfe_u32 v6, v11, 16, 1
	s_mov_b32 s70, 0xfa02000
	v_fmac_f32_e32 v13, v68, v12
	v_add3_u32 v10, v11, v6, s1
	v_add_co_u32_e32 v6, vcc, s70, v4
	v_bfe_u32 v12, v13, 16, 1
	s_nop 0
	v_addc_co_u32_e32 v7, vcc, 0, v5, vcc
	v_add3_u32 v12, v13, v12, s1
	global_store_short_d16_hi v[6:7], v10, off offset:-4096
	global_store_short_d16_hi v[6:7], v12, off
	v_mul_f32_e32 v6, v176, v14
	v_mul_f32_e32 v15, v53, v6
	v_fmac_f32_e32 v15, v69, v14
	v_bfe_u32 v6, v15, 16, 1
	v_add3_u32 v14, v15, v6, s1
	v_mul_f32_e32 v6, v232, v3
	v_exp_f32_e32 v16, v6
	s_mov_b32 s70, 0xfa03000
	v_add_co_u32_e32 v6, vcc, s70, v4
	v_mul_f32_e32 v52, v234, v3
	s_nop 0
	v_addc_co_u32_e32 v7, vcc, 0, v5, vcc
	global_store_short_d16_hi v[6:7], v14, off
	v_mul_f32_e32 v6, v176, v16
	v_mul_f32_e32 v17, v54, v6
	v_fmac_f32_e32 v17, v70, v16
	v_bfe_u32 v6, v17, 16, 1
	v_add3_u32 v16, v17, v6, s1
	v_mul_f32_e32 v6, v233, v3
	v_exp_f32_e32 v50, v6
	v_exp_f32_e32 v52, v52
	s_mov_b32 s70, 0xfa09000
	v_add_co_u32_e32 v6, vcc, s70, v4
	v_mul_f32_e32 v51, v176, v50
	v_mul_f32_e32 v51, v55, v51
	v_fmac_f32_e32 v51, v71, v50
	v_bfe_u32 v50, v51, 16, 1
	v_addc_co_u32_e32 v7, vcc, 0, v5, vcc
	v_add3_u32 v50, v51, v50, s1
	global_store_short_d16_hi v[6:7], v16, off offset:-4096
	global_store_short_d16_hi v[6:7], v50, off
	v_mul_f32_e32 v6, v176, v52
	v_mul_f32_e32 v53, v56, v6
	v_fmac_f32_e32 v53, v72, v52
	v_bfe_u32 v6, v53, 16, 1
	v_add3_u32 v52, v53, v6, s1
	v_mul_f32_e32 v6, v235, v3
	v_exp_f32_e32 v54, v6
	v_mul_f32_e32 v56, v236, v3
	v_exp_f32_e32 v56, v56
	s_mov_b32 s70, 0xfa0b000
	v_mul_f32_e32 v55, v176, v54
	v_mul_f32_e32 v55, v57, v55
	v_fmac_f32_e32 v55, v73, v54
	v_add_co_u32_e32 v6, vcc, s70, v4
	v_bfe_u32 v54, v55, 16, 1
	s_nop 0
	v_addc_co_u32_e32 v7, vcc, 0, v5, vcc
	v_add3_u32 v54, v55, v54, s1
	global_store_short_d16_hi v[6:7], v52, off offset:-4096
	global_store_short_d16_hi v[6:7], v54, off
	v_mul_f32_e32 v6, v176, v56
	v_mul_f32_e32 v57, v58, v6
	v_fmac_f32_e32 v57, v74, v56
	v_bfe_u32 v6, v57, 16, 1
	v_add3_u32 v56, v57, v6, s1
	v_mul_f32_e32 v6, v237, v3
	v_exp_f32_e32 v58, v6
	s_mov_b32 s70, 0xfa11000
	v_add_co_u32_e32 v6, vcc, s70, v4
	v_mul_f32_e32 v66, v176, v58
	v_mul_f32_e32 v59, v59, v66
	v_mul_f32_e32 v66, v238, v3
	v_exp_f32_e32 v66, v66
	v_fmac_f32_e32 v59, v75, v58
	v_bfe_u32 v58, v59, 16, 1
	v_addc_co_u32_e32 v7, vcc, 0, v5, vcc
	v_add3_u32 v58, v59, v58, s1
	global_store_short_d16_hi v[6:7], v56, off offset:-4096
	global_store_short_d16_hi v[6:7], v58, off
	v_mul_f32_e32 v6, v176, v66
	v_mul_f32_e32 v60, v60, v6
	v_fmac_f32_e32 v60, v76, v66
	v_bfe_u32 v6, v60, 16, 1
	v_add3_u32 v66, v60, v6, s1
	v_mul_f32_e32 v6, v239, v3
	v_exp_f32_e32 v67, v6
	s_mov_b32 s70, 0xfa13000
	v_add_co_u32_e32 v6, vcc, s70, v4
	v_mul_f32_e32 v68, v176, v67
	v_mul_f32_e32 v61, v61, v68
	v_mul_f32_e32 v68, v240, v3
	v_exp_f32_e32 v68, v68
	v_fmac_f32_e32 v61, v77, v67
	v_bfe_u32 v67, v61, 16, 1
	v_addc_co_u32_e32 v7, vcc, 0, v5, vcc
	v_add3_u32 v67, v61, v67, s1
	global_store_short_d16_hi v[6:7], v66, off offset:-4096
	global_store_short_d16_hi v[6:7], v67, off
	v_mul_f32_e32 v6, v176, v68
	v_mul_f32_e32 v62, v62, v6
	v_fmac_f32_e32 v62, v78, v68
	v_bfe_u32 v6, v62, 16, 1
	v_add3_u32 v68, v62, v6, s1
	v_mul_f32_e32 v6, v241, v3
	v_exp_f32_e32 v69, v6
	s_mov_b32 s70, 0xfa19000
	v_add_co_u32_e32 v6, vcc, s70, v4
	v_mul_f32_e32 v70, v176, v69
	v_mul_f32_e32 v63, v63, v70
	v_mul_f32_e32 v70, v242, v3
	v_mul_f32_e32 v3, v243, v3
	v_exp_f32_e32 v70, v70
	v_exp_f32_e32 v3, v3
	v_fmac_f32_e32 v63, v79, v69
	v_bfe_u32 v69, v63, 16, 1
	v_addc_co_u32_e32 v7, vcc, 0, v5, vcc
	v_add3_u32 v69, v63, v69, s1
	global_store_short_d16_hi v[6:7], v68, off offset:-4096
	global_store_short_d16_hi v[6:7], v69, off
	v_mul_f32_e32 v7, v176, v70
	v_mul_f32_e32 v69, v176, v3
	v_mul_f32_e32 v7, v64, v7
	v_mul_f32_e32 v65, v65, v69
	v_fmac_f32_e32 v7, v80, v70
	s_mov_b32 s70, 0xfa1b000
	v_fmac_f32_e32 v65, v81, v3
	v_bfe_u32 v64, v7, 16, 1
	v_add_co_u32_e32 v4, vcc, s70, v4
	v_bfe_u32 v3, v65, 16, 1
	v_mul_f32_e32 v9, v8, v8
	v_mul_f32_e32 v10, v11, v11
	v_add3_u32 v64, v7, v64, s1
	v_addc_co_u32_e32 v5, vcc, 0, v5, vcc
	v_add3_u32 v3, v65, v3, s1
	v_mul_f32_e32 v12, v13, v13
	v_mul_f32_e32 v14, v15, v15
	v_mul_f32_e32 v16, v17, v17
	v_mul_f32_e32 v50, v51, v51
	global_store_short_d16_hi v[4:5], v64, off offset:-4096
	global_store_short_d16_hi v[4:5], v3, off
	v_mov_b32_dpp v4, v9 row_shr:1 row_mask:0xf bank_mask:0xf bound_ctrl:1
	v_mov_b32_dpp v5, v10 row_shr:1 row_mask:0xf bank_mask:0xf bound_ctrl:1
	v_mul_f32_e32 v52, v53, v53
	v_mul_f32_e32 v54, v55, v55
	v_mul_f32_e32 v56, v57, v57
	v_mul_f32_e32 v58, v59, v59
	v_mul_f32_e32 v66, v60, v60
	v_mul_f32_e32 v67, v61, v61
	v_mul_f32_e32 v68, v62, v62
	v_mul_f32_e32 v6, v63, v63
	v_mul_f32_e32 v64, v7, v7
	v_mul_f32_e32 v3, v65, v65
	v_fmac_f32_e32 v4, v8, v8
	v_fmac_f32_e32 v5, v11, v11
	v_mov_b32_dpp v8, v12 row_shr:1 row_mask:0xf bank_mask:0xf bound_ctrl:1
	v_mov_b32_dpp v9, v14 row_shr:1 row_mask:0xf bank_mask:0xf bound_ctrl:1
	v_mov_b32_dpp v10, v16 row_shr:1 row_mask:0xf bank_mask:0xf bound_ctrl:1
	v_mov_b32_dpp v11, v50 row_shr:1 row_mask:0xf bank_mask:0xf bound_ctrl:1
	v_fmac_f32_e32 v8, v13, v13
	v_fmac_f32_e32 v9, v15, v15
	v_fmac_f32_e32 v10, v17, v17
	v_fmac_f32_e32 v11, v51, v51
	v_mov_b32_dpp v12, v52 row_shr:1 row_mask:0xf bank_mask:0xf bound_ctrl:1
	v_mov_b32_dpp v13, v54 row_shr:1 row_mask:0xf bank_mask:0xf bound_ctrl:1
	v_mov_b32_dpp v14, v56 row_shr:1 row_mask:0xf bank_mask:0xf bound_ctrl:1
	v_mov_b32_dpp v15, v58 row_shr:1 row_mask:0xf bank_mask:0xf bound_ctrl:1
	v_mov_b32_dpp v16, v66 row_shr:1 row_mask:0xf bank_mask:0xf bound_ctrl:1
	v_mov_b32_dpp v17, v67 row_shr:1 row_mask:0xf bank_mask:0xf bound_ctrl:1
	v_mov_b32_dpp v50, v68 row_shr:1 row_mask:0xf bank_mask:0xf bound_ctrl:1
	v_mov_b32_dpp v6, v6 row_shr:1 row_mask:0xf bank_mask:0xf bound_ctrl:1
	v_mov_b32_dpp v51, v64 row_shr:1 row_mask:0xf bank_mask:0xf bound_ctrl:1
	v_mov_b32_dpp v3, v3 row_shr:1 row_mask:0xf bank_mask:0xf bound_ctrl:1
	v_fmac_f32_e32 v12, v53, v53
	v_fmac_f32_e32 v13, v55, v55
	v_fmac_f32_e32 v14, v57, v57
	v_fmac_f32_e32 v15, v59, v59
	v_fmac_f32_e32 v16, v60, v60
	v_fmac_f32_e32 v17, v61, v61
	v_fmac_f32_e32 v50, v62, v62
	v_fmac_f32_e32 v6, v63, v63
	v_fmac_f32_e32 v51, v7, v7
	v_fmac_f32_e32 v3, v65, v65
	v_add_f32_dpp v4, v4, v4 row_shr:2 row_mask:0xf bank_mask:0xf bound_ctrl:1
	v_add_f32_dpp v5, v5, v5 row_shr:2 row_mask:0xf bank_mask:0xf bound_ctrl:1
	v_add_f32_dpp v7, v8, v8 row_shr:2 row_mask:0xf bank_mask:0xf bound_ctrl:1
	v_add_f32_dpp v8, v9, v9 row_shr:2 row_mask:0xf bank_mask:0xf bound_ctrl:1
	v_add_f32_dpp v9, v10, v10 row_shr:2 row_mask:0xf bank_mask:0xf bound_ctrl:1
	v_add_f32_dpp v10, v11, v11 row_shr:2 row_mask:0xf bank_mask:0xf bound_ctrl:1
	v_add_f32_dpp v11, v12, v12 row_shr:2 row_mask:0xf bank_mask:0xf bound_ctrl:1
	v_add_f32_dpp v12, v13, v13 row_shr:2 row_mask:0xf bank_mask:0xf bound_ctrl:1
	v_add_f32_dpp v13, v14, v14 row_shr:2 row_mask:0xf bank_mask:0xf bound_ctrl:1
	v_add_f32_dpp v14, v15, v15 row_shr:2 row_mask:0xf bank_mask:0xf bound_ctrl:1
	v_add_f32_dpp v15, v16, v16 row_shr:2 row_mask:0xf bank_mask:0xf bound_ctrl:1
	v_add_f32_dpp v16, v17, v17 row_shr:2 row_mask:0xf bank_mask:0xf bound_ctrl:1
	v_add_f32_dpp v17, v50, v50 row_shr:2 row_mask:0xf bank_mask:0xf bound_ctrl:1
	v_add_f32_dpp v6, v6, v6 row_shr:2 row_mask:0xf bank_mask:0xf bound_ctrl:1
	v_add_f32_dpp v50, v51, v51 row_shr:2 row_mask:0xf bank_mask:0xf bound_ctrl:1
	v_add_f32_dpp v3, v3, v3 row_shr:2 row_mask:0xf bank_mask:0xf bound_ctrl:1
	v_add_f32_dpp v4, v4, v4 row_shr:4 row_mask:0xf bank_mask:0xf bound_ctrl:1
	v_add_f32_dpp v5, v5, v5 row_shr:4 row_mask:0xf bank_mask:0xf bound_ctrl:1
	v_add_f32_dpp v7, v7, v7 row_shr:4 row_mask:0xf bank_mask:0xf bound_ctrl:1
	v_add_f32_dpp v8, v8, v8 row_shr:4 row_mask:0xf bank_mask:0xf bound_ctrl:1
	v_add_f32_dpp v9, v9, v9 row_shr:4 row_mask:0xf bank_mask:0xf bound_ctrl:1
	v_add_f32_dpp v10, v10, v10 row_shr:4 row_mask:0xf bank_mask:0xf bound_ctrl:1
	v_add_f32_dpp v11, v11, v11 row_shr:4 row_mask:0xf bank_mask:0xf bound_ctrl:1
	v_add_f32_dpp v12, v12, v12 row_shr:4 row_mask:0xf bank_mask:0xf bound_ctrl:1
	v_add_f32_dpp v13, v13, v13 row_shr:4 row_mask:0xf bank_mask:0xf bound_ctrl:1
	v_add_f32_dpp v14, v14, v14 row_shr:4 row_mask:0xf bank_mask:0xf bound_ctrl:1
	v_add_f32_dpp v15, v15, v15 row_shr:4 row_mask:0xf bank_mask:0xf bound_ctrl:1
	v_add_f32_dpp v16, v16, v16 row_shr:4 row_mask:0xf bank_mask:0xf bound_ctrl:1
	v_add_f32_dpp v17, v17, v17 row_shr:4 row_mask:0xf bank_mask:0xf bound_ctrl:1
	v_add_f32_dpp v51, v6, v6 row_shr:4 row_mask:0xf bank_mask:0xf bound_ctrl:1
	v_add_f32_dpp v53, v50, v50 row_shr:4 row_mask:0xf bank_mask:0xf bound_ctrl:1
	v_add_f32_dpp v54, v3, v3 row_shr:4 row_mask:0xf bank_mask:0xf bound_ctrl:1
	v_add_f32_dpp v3, v4, v4 row_shr:8 row_mask:0xf bank_mask:0xf bound_ctrl:1
	v_add_f32_dpp v4, v5, v5 row_shr:8 row_mask:0xf bank_mask:0xf bound_ctrl:1
	v_add_f32_dpp v5, v7, v7 row_shr:8 row_mask:0xf bank_mask:0xf bound_ctrl:1
	v_add_f32_dpp v6, v8, v8 row_shr:8 row_mask:0xf bank_mask:0xf bound_ctrl:1
	v_add_f32_dpp v7, v9, v9 row_shr:8 row_mask:0xf bank_mask:0xf bound_ctrl:1
	v_add_f32_dpp v8, v10, v10 row_shr:8 row_mask:0xf bank_mask:0xf bound_ctrl:1
	v_add_f32_dpp v9, v11, v11 row_shr:8 row_mask:0xf bank_mask:0xf bound_ctrl:1
	v_add_f32_dpp v10, v12, v12 row_shr:8 row_mask:0xf bank_mask:0xf bound_ctrl:1
	v_add_f32_dpp v11, v13, v13 row_shr:8 row_mask:0xf bank_mask:0xf bound_ctrl:1
	v_add_f32_dpp v13, v14, v14 row_shr:8 row_mask:0xf bank_mask:0xf bound_ctrl:1
	v_add_f32_dpp v15, v15, v15 row_shr:8 row_mask:0xf bank_mask:0xf bound_ctrl:1
	v_add_f32_dpp v16, v16, v16 row_shr:8 row_mask:0xf bank_mask:0xf bound_ctrl:1
	v_add_f32_dpp v50, v17, v17 row_shr:8 row_mask:0xf bank_mask:0xf bound_ctrl:1
	v_add_f32_dpp v52, v51, v51 row_shr:8 row_mask:0xf bank_mask:0xf bound_ctrl:1
	v_add_f32_dpp v53, v53, v53 row_shr:8 row_mask:0xf bank_mask:0xf bound_ctrl:1
	v_add_f32_dpp v55, v54, v54 row_shr:8 row_mask:0xf bank_mask:0xf bound_ctrl:1
	v_mov_b32_dpp v12, v3 quad_perm:[0,1,2,3] row_mask:0xf bank_mask:0x8
	v_mov_b32_dpp v12, v4 row_shl:1 row_mask:0xf bank_mask:0x8
	v_mov_b32_dpp v12, v5 row_shl:2 row_mask:0xf bank_mask:0x8
	v_mov_b32_dpp v12, v6 row_shl:3 row_mask:0xf bank_mask:0x8
	v_mov_b32_dpp v12, v7 row_shl:4 row_mask:0xf bank_mask:0x4
	v_mov_b32_dpp v12, v8 row_shl:5 row_mask:0xf bank_mask:0x4
	v_mov_b32_dpp v12, v9 row_shl:6 row_mask:0xf bank_mask:0x4
	v_mov_b32_dpp v12, v10 row_shl:7 row_mask:0xf bank_mask:0x4
	v_mov_b32_dpp v12, v11 row_shl:8 row_mask:0xf bank_mask:0x2
	v_mov_b32_dpp v12, v13 row_shl:9 row_mask:0xf bank_mask:0x2
	v_mov_b32_dpp v12, v15 row_shl:10 row_mask:0xf bank_mask:0x2
	v_mov_b32_dpp v12, v16 row_shl:11 row_mask:0xf bank_mask:0x2
	v_mov_b32_dpp v12, v50 row_shl:12 row_mask:0xf bank_mask:0x1
	v_mov_b32_dpp v12, v52 row_shl:13 row_mask:0xf bank_mask:0x1
	v_mov_b32_dpp v12, v53 row_shl:14 row_mask:0xf bank_mask:0x1
	v_mov_b32_dpp v12, v55 row_shl:15 row_mask:0xf bank_mask:0x1
	v_mov_b32_e32 v14, v12
	v_and_b32_e32 v50, 15, v0
	v_xor_b32_e32 v50, 15, v50
	v_lshrrev_b32_e32 v51, 2, v50
	v_and_b32_e32 v50, 3, v50
	v_lshlrev_b32_e32 v51, 11, v51
	v_lshl_or_b32 v50, v50, 8, v51
	v_add_u32_e32 v50, 0x200000, v50
	v_lshl_add_u64 v[4:5], s[82:83], 0, v[182:183]
	v_permlane16_swap_b32_e32 v12, v14
	v_add_co_u32_e32 v4, vcc, v4, v50
	v_add_f32_e32 v12, v12, v14
	s_nop 0
	v_addc_co_u32_e32 v5, vcc, 0, v5, vcc
	s_mov_b64 s[70:71], exec
	s_mov_b32 exec_lo, 0xffff
	s_mov_b32 exec_hi, 0xffff
	global_store_dword v[4:5], v12, off
	s_branch .LBB0_592
